# NA tile loop: wave-uniform branch test trimmed to s_or+scc branch, packed f32 offset subtracts split into scalar ops, ones row-sum MFMAs issued ahead of the V waits, persistent ones operand
# speedup vs baseline: 1.0039x; 1.0039x over previous
.LBB0_533:
	s_add_i32 s20, s31, s83
	s_add_i32 s20, s20, -2
	s_cmp_lt_i32 s0, s34
	s_cselect_b64 s[0:1], -1, 0
	s_cmp_le_u32 s68, s20
	s_cselect_b64 s[10:11], -1, 0
	s_or_b64 s[10:11], s[8:9], s[10:11]
	s_cmp_le_u32 s20, s74
	s_cselect_b64 s[12:13], -1, 0
	s_and_b64 s[10:11], s[10:11], s[12:13]
	s_and_b64 s[12:13], s[0:1], s[10:11]
	s_andn2_b64 vcc, exec, s[12:13]
	s_cbranch_vccz .Lna_win
	s_xor_b64 s[0:1], s[0:1], -1
	s_or_b64 s[10:11], s[0:1], s[10:11]
	s_and_b64 vcc, exec, s[10:11]
	s_cbranch_vccz .Lna_next
	s_and_b32 s10, s51, 0xc000
	s_add_i32 s10, s10, 0
	v_add_u32_e32 v0, s10, v235
	v_add_u32_e32 v2, v0, v241
	ds_read_b128 v[80:83], v2
	ds_read_b128 v[84:87], v2 offset:4096
	v_add_u32_e32 v2, v0, v242
	ds_read_b128 v[88:91], v2
	ds_read_b128 v[92:95], v2 offset:4096
	v_add_u32_e32 v2, v0, v243
	v_add_u32_e32 v0, v0, v244
	ds_read_b128 v[96:99], v2
	ds_read_b128 v[100:103], v2 offset:4096
	ds_read_b128 v[104:107], v0
	ds_read_b128 v[108:111], v0 offset:4096
	v_add_u32_e32 v0, s10, v238
	ds_read_b64_tr_b16 v[192:193], v0 offset:8192
	ds_read_b64_tr_b16 v[194:195], v0 offset:8704
	ds_read_b64_tr_b16 v[10:11], v0 offset:9216
	ds_read_b64_tr_b16 v[12:13], v0 offset:9728
	ds_read_b64_tr_b16 v[6:7], v0 offset:10240
	ds_read_b64_tr_b16 v[8:9], v0 offset:10752
	ds_read_b64_tr_b16 v[2:3], v0 offset:11264
	ds_read_b64_tr_b16 v[4:5], v0 offset:11776
	s_setprio 1
	s_waitcnt lgkmcnt(14)
	v_mfma_f32_32x32x16_bf16 v[144:159], v[80:83], v[188:191], v[64:79]
	v_mfma_f32_32x32x16_bf16 v[128:143], v[84:87], v[188:191], v[64:79]
	s_waitcnt lgkmcnt(13)
	v_mfma_f32_32x32x16_bf16 v[144:159], v[88:91], v[184:187], v[144:159]
	s_waitcnt lgkmcnt(12)
	v_mfma_f32_32x32x16_bf16 v[128:143], v[92:95], v[184:187], v[128:143]
	s_waitcnt lgkmcnt(11)
	v_mfma_f32_32x32x16_bf16 v[144:159], v[96:99], v[180:183], v[144:159]
	s_waitcnt lgkmcnt(10)
	v_mfma_f32_32x32x16_bf16 v[128:143], v[100:103], v[180:183], v[128:143]
	s_waitcnt lgkmcnt(9)
	v_mfma_f32_32x32x16_bf16 v[144:159], v[104:107], v[176:179], v[144:159]
	s_waitcnt lgkmcnt(8)
	v_mfma_f32_32x32x16_bf16 v[128:143], v[108:111], v[176:179], v[128:143]
	s_setprio 0
	v_max3_f32 v14, v144, v145, v146
	v_max3_f32 v15, v147, v148, v149
	v_max3_f32 v80, v150, v151, v152
	v_max3_f32 v81, v153, v154, v155
	v_max3_f32 v82, v156, v157, v158
	v_max3_f32 v83, v128, v129, v130
	v_max3_f32 v84, v131, v132, v133
	v_max3_f32 v85, v134, v135, v136
	s_nop 0
	v_max3_f32 v14, v14, v15, v80
	v_max3_f32 v86, v137, v138, v139
	v_max3_f32 v15, v81, v82, v159
	v_max3_f32 v87, v140, v141, v142
	s_xor_b64 s[10:11], s[46:47], -1
	v_max3_f32 v80, v83, v84, v85
	v_max3_f32 v81, v86, v87, v143
	s_nop 0
	v_max3_f32 v14, v14, v15, v80
	v_max_f32_e32 v14, v14, v81
	v_mov_b32_e32 v15, v14
	s_nop 1
	v_permlane32_swap_b32_e32 v15, v14
	v_max_f32_e32 v14, v14, v15
	v_cmp_lt_f32_e32 vcc, s27, v14
	s_or_b64 s[10:11], vcc, s[10:11]
	s_cbranch_scc0 .Lna_547
	v_max_f32_e32 v15, v14, v14
	v_max_f32_e32 v15, 0, v15
	v_cndmask_b32_e64 v80, v14, v15, s[46:47]
	v_exp_f32_e64 v15, -v80
	v_add_f32_e32 v212, v212, v80
	v_xor_b32_e32 v64, 0x80000000, v212
	v_pk_add_f32 v[144:145], v[144:145], v[80:81] op_sel_hi:[1,0] neg_lo:[0,1] neg_hi:[0,1]
	v_cndmask_b32_e64 v160, 0, v15, s[46:47]
	v_pk_add_f32 v[128:129], v[128:129], v[80:81] op_sel_hi:[1,0] neg_lo:[0,1] neg_hi:[0,1]
	v_pk_add_f32 v[146:147], v[146:147], v[80:81] op_sel_hi:[1,0] neg_lo:[0,1] neg_hi:[0,1]
	v_pk_add_f32 v[130:131], v[130:131], v[80:81] op_sel_hi:[1,0] neg_lo:[0,1] neg_hi:[0,1]
	v_pk_add_f32 v[148:149], v[148:149], v[80:81] op_sel_hi:[1,0] neg_lo:[0,1] neg_hi:[0,1]
	v_pk_add_f32 v[132:133], v[132:133], v[80:81] op_sel_hi:[1,0] neg_lo:[0,1] neg_hi:[0,1]
	v_pk_add_f32 v[150:151], v[150:151], v[80:81] op_sel_hi:[1,0] neg_lo:[0,1] neg_hi:[0,1]
	v_pk_add_f32 v[134:135], v[134:135], v[80:81] op_sel_hi:[1,0] neg_lo:[0,1] neg_hi:[0,1]
	v_pk_add_f32 v[152:153], v[152:153], v[80:81] op_sel_hi:[1,0] neg_lo:[0,1] neg_hi:[0,1]
	v_pk_add_f32 v[136:137], v[136:137], v[80:81] op_sel_hi:[1,0] neg_lo:[0,1] neg_hi:[0,1]
	v_pk_add_f32 v[154:155], v[154:155], v[80:81] op_sel_hi:[1,0] neg_lo:[0,1] neg_hi:[0,1]
	v_pk_add_f32 v[138:139], v[138:139], v[80:81] op_sel_hi:[1,0] neg_lo:[0,1] neg_hi:[0,1]
	v_pk_add_f32 v[156:157], v[156:157], v[80:81] op_sel_hi:[1,0] neg_lo:[0,1] neg_hi:[0,1]
	v_pk_add_f32 v[140:141], v[140:141], v[80:81] op_sel_hi:[1,0] neg_lo:[0,1] neg_hi:[0,1]
	v_pk_add_f32 v[158:159], v[158:159], v[80:81] op_sel_hi:[1,0] neg_lo:[0,1] neg_hi:[0,1]
	v_pk_add_f32 v[142:143], v[142:143], v[80:81] op_sel_hi:[1,0] neg_lo:[0,1] neg_hi:[0,1]
	v_pk_mul_f32 v[30:31], v[30:31], v[160:161] op_sel_hi:[1,0]
	v_pk_mul_f32 v[28:29], v[28:29], v[160:161] op_sel_hi:[1,0]
	v_pk_mul_f32 v[26:27], v[26:27], v[160:161] op_sel_hi:[1,0]
	v_pk_mul_f32 v[24:25], v[24:25], v[160:161] op_sel_hi:[1,0]
	v_pk_mul_f32 v[22:23], v[22:23], v[160:161] op_sel_hi:[1,0]
	v_pk_mul_f32 v[20:21], v[20:21], v[160:161] op_sel_hi:[1,0]
	v_pk_mul_f32 v[18:19], v[18:19], v[160:161] op_sel_hi:[1,0]
	v_pk_mul_f32 v[16:17], v[16:17], v[160:161] op_sel_hi:[1,0]
	v_pk_mul_f32 v[46:47], v[46:47], v[160:161] op_sel_hi:[1,0]
	v_pk_mul_f32 v[44:45], v[44:45], v[160:161] op_sel_hi:[1,0]
	v_pk_mul_f32 v[42:43], v[42:43], v[160:161] op_sel_hi:[1,0]
	v_pk_mul_f32 v[40:41], v[40:41], v[160:161] op_sel_hi:[1,0]
	v_pk_mul_f32 v[38:39], v[38:39], v[160:161] op_sel_hi:[1,0]
	v_pk_mul_f32 v[36:37], v[36:37], v[160:161] op_sel_hi:[1,0]
	v_pk_mul_f32 v[34:35], v[34:35], v[160:161] op_sel_hi:[1,0]
	v_pk_mul_f32 v[32:33], v[32:33], v[160:161] op_sel_hi:[1,0]
	v_mov_b32_e32 v65, v64
	v_mov_b32_e32 v66, v64
	v_mov_b32_e32 v67, v64
	v_mov_b32_e32 v68, v64
	v_mov_b32_e32 v69, v64
	v_mov_b32_e32 v70, v64
	v_mov_b32_e32 v71, v64
	v_mov_b32_e32 v72, v64
	v_mov_b32_e32 v73, v64
	v_mov_b32_e32 v74, v64
	v_mov_b32_e32 v75, v64
	v_mov_b32_e32 v76, v64
	v_mov_b32_e32 v77, v64
	v_mov_b32_e32 v78, v64
	v_mov_b32_e32 v79, v64
	v_pk_mul_f32 v[62:63], v[62:63], v[160:161] op_sel_hi:[1,0]
	v_pk_mul_f32 v[60:61], v[60:61], v[160:161] op_sel_hi:[1,0]
	v_pk_mul_f32 v[58:59], v[58:59], v[160:161] op_sel_hi:[1,0]
	v_pk_mul_f32 v[56:57], v[56:57], v[160:161] op_sel_hi:[1,0]
	v_pk_mul_f32 v[54:55], v[54:55], v[160:161] op_sel_hi:[1,0]
	v_pk_mul_f32 v[52:53], v[52:53], v[160:161] op_sel_hi:[1,0]
	v_pk_mul_f32 v[50:51], v[50:51], v[160:161] op_sel_hi:[1,0]
	v_pk_mul_f32 v[48:49], v[48:49], v[160:161] op_sel_hi:[1,0]
	s_or_b64 s[46:47], s[46:47], exec
.Lna_547:
	v_exp_f32_e32 v15, v144
	v_exp_f32_e32 v144, v128
	v_exp_f32_e32 v128, v145
	v_exp_f32_e32 v129, v129
	v_exp_f32_e32 v145, v146
	v_exp_f32_e32 v130, v130
	v_exp_f32_e32 v146, v147
	v_exp_f32_e32 v131, v131
	v_exp_f32_e32 v147, v148
	v_exp_f32_e32 v148, v132
	v_exp_f32_e32 v149, v149
	v_exp_f32_e32 v218, v133
	v_exp_f32_e32 v150, v150
	v_exp_f32_e32 v219, v134
	v_exp_f32_e32 v151, v151
	v_exp_f32_e32 v220, v135
	v_exp_f32_e32 v132, v152
	v_exp_f32_e32 v133, v136
	v_exp_f32_e32 v134, v153
	v_exp_f32_e32 v135, v137
	v_exp_f32_e32 v137, v154
	v_exp_f32_e32 v138, v138
	v_exp_f32_e32 v152, v155
	v_exp_f32_e32 v139, v139
	v_exp_f32_e32 v153, v156
	v_exp_f32_e32 v154, v140
	v_exp_f32_e32 v155, v157
	v_exp_f32_e32 v156, v141
	v_exp_f32_e32 v157, v158
	v_exp_f32_e32 v158, v142
	v_exp_f32_e32 v159, v159
	v_exp_f32_e32 v143, v143
	v_cvt_pk_bf16_f32 v128, v15, v128
	v_cvt_pk_bf16_f32 v132, v132, v134
	v_cvt_pk_bf16_f32 v136, v144, v129
	v_cvt_pk_bf16_f32 v140, v133, v135
	v_cvt_pk_bf16_f32 v129, v145, v146
	v_cvt_pk_bf16_f32 v133, v137, v152
	v_cvt_pk_bf16_f32 v137, v130, v131
	v_cvt_pk_bf16_f32 v141, v138, v139
	v_cvt_pk_bf16_f32 v130, v147, v149
	v_cvt_pk_bf16_f32 v134, v153, v155
	v_cvt_pk_bf16_f32 v138, v148, v218
	v_cvt_pk_bf16_f32 v142, v154, v156
	v_cvt_pk_bf16_f32 v131, v150, v151
	v_cvt_pk_bf16_f32 v135, v157, v159
	v_cvt_pk_bf16_f32 v139, v219, v220
	v_cvt_pk_bf16_f32 v143, v158, v143
	ds_read_b64_tr_b16 v[144:145], v0 offset:12288
	ds_read_b64_tr_b16 v[146:147], v0 offset:12800
	ds_read_b64_tr_b16 v[148:149], v0 offset:13312
	ds_read_b64_tr_b16 v[150:151], v0 offset:13824
	ds_read_b64_tr_b16 v[152:153], v0 offset:14336
	ds_read_b64_tr_b16 v[154:155], v0 offset:14848
	ds_read_b64_tr_b16 v[156:157], v0 offset:15360
	ds_read_b64_tr_b16 v[158:159], v0 offset:15872
	s_setprio 1
	s_waitcnt lgkmcnt(8)
	v_mfma_f32_32x32x16_bf16 v[16:31], v[192:195], v[128:131], v[16:31]
	v_mfma_f32_32x32x16_bf16 v[16:31], v[10:13], v[132:135], v[16:31]
	v_mfma_f32_32x32x16_bf16 v[16:31], v[6:9], v[136:139], v[16:31]
	v_mfma_f32_32x32x16_bf16 v[16:31], v[2:5], v[140:143], v[16:31]
	v_mfma_f32_32x32x16_bf16 v[48:63], v[116:119], v[128:131], v[48:63]
	s_waitcnt lgkmcnt(6)
	v_mfma_f32_32x32x16_bf16 v[32:47], v[144:147], v[128:131], v[32:47]
	v_mfma_f32_32x32x16_bf16 v[48:63], v[116:119], v[132:135], v[48:63]
	s_waitcnt lgkmcnt(4)
	v_mfma_f32_32x32x16_bf16 v[32:47], v[148:151], v[132:135], v[32:47]
	v_mfma_f32_32x32x16_bf16 v[48:63], v[116:119], v[136:139], v[48:63]
	s_waitcnt lgkmcnt(2)
	v_mfma_f32_32x32x16_bf16 v[32:47], v[152:155], v[136:139], v[32:47]
	v_mfma_f32_32x32x16_bf16 v[48:63], v[116:119], v[140:143], v[48:63]
	s_waitcnt lgkmcnt(0)
	v_mfma_f32_32x32x16_bf16 v[32:47], v[156:159], v[140:143], v[32:47]
	s_setprio 0
	s_branch .Lna_next
.Lna_win:
	s_and_b32 s0, s51, 0xc000
	s_add_i32 s10, s0, 0
	v_cmp_lt_u32_e32 vcc, s20, v239
	v_cmp_gt_u32_e64 s[0:1], s20, v240
	v_add3_u32 v0, v249, s83, 6
	s_or_b64 s[0:1], vcc, s[0:1]
	v_cndmask_b32_e64 v0, v0, 0, s[0:1]
	v_mad_u64_u32 v[2:3], s[0:1], v0, v236, v[210:211]
	ds_read2_b32 v[80:81], v2 offset1:1
	ds_read2_b32 v[82:83], v2 offset0:2 offset1:3
	ds_read2_b32 v[84:85], v2 offset0:8 offset1:9
	ds_read2_b32 v[86:87], v2 offset0:10 offset1:11
	ds_read2_b32 v[88:89], v2 offset0:16 offset1:17
	ds_read2_b32 v[90:91], v2 offset0:18 offset1:19
	ds_read2_b32 v[92:93], v2 offset0:24 offset1:25
	ds_read2_b32 v[94:95], v2 offset0:26 offset1:27
	v_add_u32_e32 v0, s10, v237
	v_add_u32_e32 v2, v0, v245
	v_add_u32_e32 v3, v0, v246
	ds_read_b128 v[100:103], v2
	ds_read_b128 v[104:107], v3
	v_add_u32_e32 v2, v0, v247
	v_add_u32_e32 v0, v0, v248
	ds_read_b128 v[108:111], v2
	ds_read_b128 v[112:115], v0
	s_add_i32 s0, s75, s10
	v_add_u32_e32 v0, s0, v238
	ds_read_b64_tr_b16 v[96:97], v0 offset:8192
	ds_read_b64_tr_b16 v[98:99], v0 offset:8704
	ds_read_b64_tr_b16 v[2:3], v0 offset:9216
	ds_read_b64_tr_b16 v[4:5], v0 offset:9728
	ds_read_b64_tr_b16 v[10:11], v0 offset:12288
	ds_read_b64_tr_b16 v[12:13], v0 offset:12800
	ds_read_b64_tr_b16 v[6:7], v0 offset:13312
	ds_read_b64_tr_b16 v[8:9], v0 offset:13824
	s_setprio 1
	s_waitcnt lgkmcnt(11)
	v_mfma_f32_32x32x16_bf16 v[80:95], v[100:103], v[188:191], v[80:95]
	s_waitcnt lgkmcnt(10)
	v_mfma_f32_32x32x16_bf16 v[80:95], v[104:107], v[184:187], v[80:95]
	s_waitcnt lgkmcnt(9)
	v_mfma_f32_32x32x16_bf16 v[80:95], v[108:111], v[180:183], v[80:95]
	s_waitcnt lgkmcnt(8)
	v_mfma_f32_32x32x16_bf16 v[80:95], v[112:115], v[176:179], v[80:95]
	s_setprio 0
	s_nop 10
	v_sub_f32_e32 v14, v80, v212
	v_sub_f32_e32 v15, v81, v212
	v_sub_f32_e32 v80, v82, v212
	v_sub_f32_e32 v81, v83, v212
	v_sub_f32_e32 v82, v84, v212
	v_sub_f32_e32 v83, v85, v212
	v_sub_f32_e32 v84, v86, v212
	v_sub_f32_e32 v85, v87, v212
	v_sub_f32_e32 v86, v88, v212
	v_sub_f32_e32 v87, v89, v212
	v_sub_f32_e32 v88, v90, v212
	v_sub_f32_e32 v89, v91, v212
	v_sub_f32_e32 v90, v92, v212
	v_sub_f32_e32 v91, v93, v212
	v_sub_f32_e32 v92, v94, v212
	v_sub_f32_e32 v93, v95, v212
	v_max3_f32 v0, v14, v15, v80
	v_max3_f32 v94, v81, v82, v83
	v_max3_f32 v95, v84, v85, v86
	v_max3_f32 v100, v87, v88, v89
	s_mov_b32 s0, 0xefa18f08
	v_max3_f32 v101, v90, v91, v92
	v_max3_f32 v0, v0, v94, v95
	v_max3_f32 v94, v100, v101, v93
	v_max3_f32 v0, v0, v94, v216
	s_xor_b64 s[10:11], s[46:47], -1
	v_mov_b32_e32 v94, v0
	s_nop 1
	v_permlane32_swap_b32_e32 v94, v0
	v_max_f32_e32 v0, v0, v94
	v_cmp_lt_f32_e64 s[0:1], s0, v0
	v_cmp_lt_f32_e32 vcc, s27, v0
	s_and_b64 s[10:11], s[0:1], s[10:11]
	s_or_b64 s[10:11], vcc, s[10:11]
	s_cbranch_scc0 .Lna_541
	v_max_f32_e32 v64, v0, v0
	v_max_f32_e32 v64, 0, v64
	v_cndmask_b32_e64 v0, 0, v0, s[0:1]
	v_cndmask_b32_e64 v65, v0, v64, s[46:47]
	v_exp_f32_e64 v0, -v65
	v_add_f32_e32 v212, v212, v65
	s_or_b64 s[0:1], s[46:47], s[0:1]
	v_xor_b32_e32 v64, 0x80000000, v212
	v_cndmask_b32_e64 v0, 0, v0, s[46:47]
	s_andn2_b64 s[10:11], s[46:47], exec
	s_and_b64 s[0:1], s[0:1], exec
	v_sub_f32_e32 v14, v14, v65
	v_sub_f32_e32 v15, v15, v65
	v_sub_f32_e32 v80, v80, v65
	v_sub_f32_e32 v81, v81, v65
	v_sub_f32_e32 v82, v82, v65
	v_sub_f32_e32 v83, v83, v65
	v_sub_f32_e32 v84, v84, v65
	v_sub_f32_e32 v85, v85, v65
	v_sub_f32_e32 v86, v86, v65
	v_sub_f32_e32 v87, v87, v65
	v_sub_f32_e32 v88, v88, v65
	v_sub_f32_e32 v89, v89, v65
	v_sub_f32_e32 v90, v90, v65
	v_sub_f32_e32 v91, v91, v65
	v_sub_f32_e32 v92, v92, v65
	v_sub_f32_e32 v93, v93, v65
	v_pk_mul_f32 v[62:63], v[62:63], v[0:1] op_sel_hi:[1,0]
	v_pk_mul_f32 v[60:61], v[60:61], v[0:1] op_sel_hi:[1,0]
	v_pk_mul_f32 v[58:59], v[58:59], v[0:1] op_sel_hi:[1,0]
	v_pk_mul_f32 v[56:57], v[56:57], v[0:1] op_sel_hi:[1,0]
	v_pk_mul_f32 v[54:55], v[54:55], v[0:1] op_sel_hi:[1,0]
	v_pk_mul_f32 v[52:53], v[52:53], v[0:1] op_sel_hi:[1,0]
	v_pk_mul_f32 v[50:51], v[50:51], v[0:1] op_sel_hi:[1,0]
	v_pk_mul_f32 v[48:49], v[48:49], v[0:1] op_sel_hi:[1,0]
	v_pk_mul_f32 v[30:31], v[30:31], v[0:1] op_sel_hi:[1,0]
	v_pk_mul_f32 v[28:29], v[28:29], v[0:1] op_sel_hi:[1,0]
	v_pk_mul_f32 v[26:27], v[26:27], v[0:1] op_sel_hi:[1,0]
	v_pk_mul_f32 v[24:25], v[24:25], v[0:1] op_sel_hi:[1,0]
	v_pk_mul_f32 v[22:23], v[22:23], v[0:1] op_sel_hi:[1,0]
	v_pk_mul_f32 v[20:21], v[20:21], v[0:1] op_sel_hi:[1,0]
	v_pk_mul_f32 v[18:19], v[18:19], v[0:1] op_sel_hi:[1,0]
	v_pk_mul_f32 v[16:17], v[16:17], v[0:1] op_sel_hi:[1,0]
	v_pk_mul_f32 v[46:47], v[46:47], v[0:1] op_sel_hi:[1,0]
	v_pk_mul_f32 v[44:45], v[44:45], v[0:1] op_sel_hi:[1,0]
	v_pk_mul_f32 v[42:43], v[42:43], v[0:1] op_sel_hi:[1,0]
	v_pk_mul_f32 v[40:41], v[40:41], v[0:1] op_sel_hi:[1,0]
	v_pk_mul_f32 v[38:39], v[38:39], v[0:1] op_sel_hi:[1,0]
	v_pk_mul_f32 v[36:37], v[36:37], v[0:1] op_sel_hi:[1,0]
	v_pk_mul_f32 v[34:35], v[34:35], v[0:1] op_sel_hi:[1,0]
	v_pk_mul_f32 v[32:33], v[32:33], v[0:1] op_sel_hi:[1,0]
	v_mov_b32_e32 v65, v64
	v_mov_b32_e32 v66, v64
	v_mov_b32_e32 v67, v64
	v_mov_b32_e32 v68, v64
	v_mov_b32_e32 v69, v64
	v_mov_b32_e32 v70, v64
	v_mov_b32_e32 v71, v64
	v_mov_b32_e32 v72, v64
	v_mov_b32_e32 v73, v64
	v_mov_b32_e32 v74, v64
	v_mov_b32_e32 v75, v64
	v_mov_b32_e32 v76, v64
	v_mov_b32_e32 v77, v64
	v_mov_b32_e32 v78, v64
	v_mov_b32_e32 v79, v64
	s_or_b64 s[46:47], s[10:11], s[0:1]

.Lna_next:
	s_add_i32 s83, s83, 1
	s_addk_i32 s51, 0x4000
	s_add_i32 s50, s50, 64
	s_add_i32 s0, s86, s83
	s_cmp_lg_u32 s0, 2
	s_cbranch_scc1 .LBB0_528
	s_nop 15
	v_mov_b64_e32 v[80:81], v[16:17]
	v_mov_b64_e32 v[82:83], v[18:19]
	v_mov_b64_e32 v[84:85], v[20:21]
	v_mov_b64_e32 v[86:87], v[22:23]
	v_mov_b64_e32 v[88:89], v[24:25]
	v_mov_b64_e32 v[90:91], v[26:27]
	v_mov_b64_e32 v[92:93], v[28:29]
	v_mov_b64_e32 v[94:95], v[30:31]
	v_mov_b64_e32 v[96:97], v[32:33]
	v_mov_b64_e32 v[98:99], v[34:35]
	v_mov_b64_e32 v[100:101], v[36:37]
	v_mov_b64_e32 v[102:103], v[38:39]
	v_mov_b64_e32 v[104:105], v[40:41]
	v_mov_b64_e32 v[106:107], v[42:43]
	v_mov_b64_e32 v[108:109], v[44:45]
	v_mov_b64_e32 v[110:111], v[46:47]
	v_mov_b32_e32 v160, v48
	s_branch .LBB0_489
	s_nop 0
